# FFN-up phase: odd-XCD workgroups start the tile loop 48x64 cycles later
# speedup vs baseline: 1.0088x; 1.0013x over previous
.LBB0_129:
	v_and_b32_e32 v13, 15, v12
	v_lshrrev_b32_e32 v12, 1, v12
	v_and_b32_e32 v12, 24, v12
	v_lshlrev_b32_e32 v18, 1, v12
	v_lshl_or_b32 v150, s36, 6, v13
	v_lshl_or_b32 v18, v13, 6, v18
	v_lshlrev_b32_e32 v13, 2, v13
	s_lshl_b32 s6, s36, 13
	v_and_b32_e32 v19, 32, v13
	v_readlane_b32 s52, v254, 14
	v_bitop3_b32 v20, v18, s6, v19 bitop3:0xde
	s_lshl_b32 s6, s25, 5
	v_mov_b32_e32 v135, v1
	v_readlane_b32 s53, v254, 15
	s_and_b32 s25, s6, 0x60
	s_add_i32 m0, s61, 0x18000
	v_lshl_add_u64 v[2:3], v[2:3], 0, s[84:85]
	v_lshl_add_u64 v[14:15], s[52:53], 0, v[134:135]
	v_mov_b32_e32 v133, v1
	s_lshl_b32 s6, s25, 7
	s_waitcnt vmcnt(2)
	s_barrier
	global_load_lds_dwordx4 v[2:3], off
	v_lshl_add_u64 v[2:3], v[4:5], 0, s[84:85]
	s_add_i32 m0, s61, 0x1a000
	s_add_i32 s65, s61, 0x8000
	s_add_i32 s66, s61, 0xa000
	v_lshl_add_u64 v[16:17], s[52:53], 0, v[132:133]
	v_bitop3_b32 v151, v18, s6, v19 bitop3:0xde
	global_load_lds_dwordx4 v[2:3], off
	v_lshl_add_u64 v[2:3], v[14:15], 0, s[84:85]
	s_mov_b32 m0, s65
	s_add_u32 s6, s54, 0x40080
	global_load_lds_dwordx4 v[2:3], off
	v_lshl_add_u64 v[2:3], v[16:17], 0, s[84:85]
	s_mov_b32 m0, s66
	s_addc_u32 s7, s55, 0
	global_load_lds_dwordx4 v[2:3], off
	s_add_i32 m0, s61, 0x1c000
	v_lshl_add_u64 v[2:3], s[6:7], 0, v[0:1]
	global_load_lds_dwordx4 v[2:3], off
	v_lshl_add_u64 v[2:3], s[6:7], 0, v[130:131]
	s_add_i32 m0, s61, 0x1e000
	s_cmpk_lt_u32 s24, 0x100
	global_load_lds_dwordx4 v[2:3], off
	v_lshlrev_b32_e32 v2, 14, v10
	v_and_b32_e32 v2, 0xffff8000, v2
	v_lshl_add_u32 v2, v9, 11, v2
	v_and_b32_e32 v3, 1, v10
	v_lshl_or_b32 v2, v3, 6, v2
	s_cselect_b64 s[42:43], -1, 0
	s_and_b32 s6, s24, 0xffffff00
	v_lshl_add_u32 v136, v11, 1, v2
	v_lshlrev_b32_e32 v2, 14, v6
	s_add_i32 s6, s6, 0
	v_and_b32_e32 v2, 0xffff8000, v2
	s_waitcnt vmcnt(6)
	s_add_i32 s6, s6, 0x20200
	v_lshl_add_u32 v2, v7, 11, v2
	v_and_b32_e32 v3, 1, v6
	v_add_u32_e32 v152, s6, v13
	v_lshl_or_b32 v2, v3, 6, v2
	v_readlane_b32 s6, v254, 12
	v_or_b32_e32 v153, s25, v12
	v_mov_b32_e32 v137, v1
	v_lshl_add_u32 v138, v8, 1, v2
	v_mov_b32_e32 v139, v1
	s_mov_b32 s67, 0
	v_add_u32_e32 v154, 0, v20
	v_readlane_b32 s36, v254, 9
	s_mov_b32 s37, s6
	s_barrier
	v_readlane_b32 s7, v254, 13
	v_readlane_b32 s98, v252, 0
	s_bitcmp0_b32 s98, 5
	s_cbranch_scc1 .Ldephase_ffn
	s_sleep 48
